# MLA latent norm pass: decoupled-rope inputs loaded together with the row so each row costs one memory round trip instead of two
# speedup vs baseline: 1.0085x; 1.0085x over previous
; DEV unsigned f2bf(float f) { unsigned u = __builtin_bit_cast(unsigned, f); return (u + 0x7fffu + ((u >> 16) & 1u)) >> 16; }
; DEV unsigned pk2(float lo, float hi) { f32x2_ v; v.x = lo; v.y = hi; return __builtin_bit_cast(unsigned, __builtin_convertvector(v, bf16x2_)); }
; template <int layer> DEV void layer_body(const Args& args, LAS unsigned char* lds, const XcdBarrier& bar, int tid, int lane, int G, int c, int gw, int NGW, size_t gt, size_t GT) {
;     ...
;                 for (int m = gw; m < NTOK; m += NGW) {
;                     const bf16* hx = (const bf16*)(S + S2_HX) + (size_t)m * 512;
;                     const u32x2 q2 = *(const u32x2*)(hx + 4 * lane); const unsigned kv1 = *(const unsigned*)(hx + 256 + 2 * lane);
;                     float qv[4] = {__builtin_bit_cast(float, q2.x << 16), __builtin_bit_cast(float, q2.x & 0xffff0000u), __builtin_bit_cast(float, q2.y << 16), __builtin_bit_cast(float, q2.y & 0xffff0000u)};
;                     float kv[2] = {__builtin_bit_cast(float, kv1 << 16), __builtin_bit_cast(float, kv1 & 0xffff0000u)};
;                     const float sq = wave_sum(qv[0] * qv[0] + qv[1] * qv[1] + qv[2] * qv[2] + qv[3] * qv[3], lane); const float sk = wave_sum(kv[0] * kv[0] + kv[1] * kv[1], lane);
;                     const float rq = 1.f / sqrtf(sq * (1.f / 256.f) + 1e-6f), rk = 1.f / sqrtf(sk * (1.f / 128.f) + 1e-6f);
;                     const f32x4 g4 = ((const f32x4*)gq)[lane]; const float g0 = gkv[2 * lane], g1 = gkv[2 * lane + 1];
;                     u32x2 oq; oq.x = pk2(qv[0] * rq * g4.x, qv[1] * rq * g4.y); oq.y = pk2(qv[2] * rq * g4.z, qv[3] * rq * g4.w);
;                     *(u32x2*)((bf16*)(S + S2_CQN) + (size_t)m * 256 + 4 * lane) = oq;
;                     *(unsigned*)((bf16*)(S + S2_CKVN) + (size_t)m * 128 + 2 * lane) = pk2(kv[0] * rk * g0, kv[1] * rk * g1);
;                     if (lane < 16) { const int pos = m & (SEQ - 1); const float x1 = bf2f(hx[384 + lane]), x2 = bf2f(hx[400 + lane]); const float cc = cos32[pos * 16 + lane], ss = sin32[pos * 16 + lane];
;                         bf16* kr = (bf16*)(S + S2_KROPE) + (size_t)m * 32; kr[lane] = (bf16)f2bf(x1 * cc - x2 * ss); kr[16 + lane] = (bf16)f2bf(x2 * cc + x1 * ss); }
;                 }
.LBB0_1618:
	v_lshl_add_u64 v[22:23], s[50:51], 0, v[14:15]
	global_load_dword v21, v[22:23], off
	v_lshl_add_u64 v[22:23], s[50:51], 0, v[12:13]
	global_load_dwordx2 v[26:27], v[22:23], off
	s_nop 0
	flat_load_dwordx4 v[22:25], v[2:3]
	flat_load_dwordx2 v[28:29], v[4:5]
	s_and_b32 s98, s5, 0x1fff0
	v_add_u32_e32 v52, s98, v0
	v_lshl_add_u64 v[50:51], s[50:51], 0, v[16:17]
	v_ashrrev_i32_e32 v53, 31, v52
	s_mov_b64 s[98:99], 0xa800000
	v_lshlrev_b64 v[52:53], 2, v[52:53]
	v_lshl_add_u64 v[50:51], v[50:51], 0, s[98:99]
	v_lshl_add_u64 v[54:55], s[22:23], 0, v[52:53]
	v_lshl_add_u64 v[52:53], s[24:25], 0, v[52:53]
	global_load_ushort v46, v[50:51], off offset:768
	global_load_ushort v47, v[50:51], off offset:800
	global_load_dword v48, v[52:53], off
	global_load_dword v49, v[54:55], off
	s_waitcnt vmcnt(0)
	v_lshlrev_b32_e32 v34, 16, v26
	v_lshlrev_b32_e32 v30, 16, v21
	v_and_b32_e32 v31, 0xffff0000, v21
	v_and_b32_e32 v35, 0xffff0000, v26
	v_lshlrev_b32_e32 v32, 16, v27
	v_and_b32_e32 v33, 0xffff0000, v27
	v_pk_mul_f32 v[36:37], v[34:35], v[34:35]
	v_pk_mul_f32 v[38:39], v[30:31], v[30:31]
	v_pk_mul_f32 v[26:27], v[32:33], v[32:33]
	v_add_f32_e32 v21, v36, v37
	v_add_f32_e32 v36, v38, v39
	v_add_f32_e32 v21, v26, v21
	v_add_f32_e32 v21, v27, v21
	v_add_f32_dpp v26, v36, v36 quad_perm:[1,0,3,2] row_mask:0xf bank_mask:0xf bound_ctrl:1
	s_nop 0
	v_add_f32_dpp v21, v21, v21 quad_perm:[1,0,3,2] row_mask:0xf bank_mask:0xf bound_ctrl:1
	v_add_f32_dpp v26, v26, v26 quad_perm:[2,3,0,1] row_mask:0xf bank_mask:0xf bound_ctrl:1
	s_nop 0
	v_add_f32_dpp v21, v21, v21 quad_perm:[2,3,0,1] row_mask:0xf bank_mask:0xf bound_ctrl:1
	v_add_f32_dpp v26, v26, v26 row_half_mirror row_mask:0xf bank_mask:0xf bound_ctrl:1
	s_nop 0
	v_add_f32_dpp v21, v21, v21 row_half_mirror row_mask:0xf bank_mask:0xf bound_ctrl:1
	v_add_f32_dpp v26, v26, v26 row_mirror row_mask:0xf bank_mask:0xf bound_ctrl:1
	ds_bpermute_b32 v27, v18, v26
	v_add_f32_dpp v21, v21, v21 row_mirror row_mask:0xf bank_mask:0xf bound_ctrl:1
	ds_bpermute_b32 v36, v18, v21
	s_waitcnt lgkmcnt(0)
	v_add_f32_e32 v37, v26, v27
	ds_bpermute_b32 v38, v19, v37
	v_add_f32_e32 v21, v21, v36
	ds_bpermute_b32 v36, v19, v21
	v_lshl_add_u64 v[26:27], s[50:51], 0, v[10:11]
	s_waitcnt lgkmcnt(1)
	v_add_f32_e32 v37, v37, v38
	v_fmamk_f32 v37, v37, 0x3c000000, v1
	s_waitcnt lgkmcnt(0)
	v_add_f32_e32 v21, v21, v36
	v_mul_f32_e32 v36, 0x4f800000, v37
	v_cmp_gt_f32_e32 vcc, s15, v37
	v_fmamk_f32 v21, v21, 0x3b800000, v1
	v_cmp_gt_f32_e64 s[8:9], s15, v21
	v_cndmask_b32_e32 v36, v37, v36, vcc
	v_mul_f32_e32 v37, 0x4f800000, v21
	v_sqrt_f32_e32 v38, v36
	v_cndmask_b32_e64 v21, v21, v37, s[8:9]
	v_sqrt_f32_e32 v37, v21
	v_add_u32_e32 v39, -1, v38
	v_add_u32_e32 v40, 1, v38
	v_fma_f32 v41, -v39, v38, v36
	v_fma_f32 v42, -v40, v38, v36
	v_add_u32_e32 v43, -1, v37
	v_cmp_ge_f32_e64 s[10:11], 0, v41
	v_add_u32_e32 v44, 1, v37
	v_fma_f32 v41, -v44, v37, v21
	v_cndmask_b32_e64 v38, v38, v39, s[10:11]
	v_fma_f32 v39, -v43, v37, v21
	v_cmp_lt_f32_e64 s[10:11], 0, v42
	s_nop 1
	v_cndmask_b32_e64 v38, v38, v40, s[10:11]
	v_cmp_ge_f32_e64 s[10:11], 0, v39
	v_mul_f32_e32 v39, 0x37800000, v38
	v_cndmask_b32_e32 v38, v38, v39, vcc
	v_cndmask_b32_e64 v37, v37, v43, s[10:11]
	v_cmp_lt_f32_e64 s[10:11], 0, v41
	v_cmp_class_f32_e32 vcc, v36, v20
	s_nop 0
	v_cndmask_b32_e64 v37, v37, v44, s[10:11]
	v_mul_f32_e32 v39, 0x37800000, v37
	v_cndmask_b32_e32 v38, v38, v36, vcc
	v_cndmask_b32_e64 v36, v37, v39, s[8:9]
	v_cmp_class_f32_e32 vcc, v21, v20
	v_div_scale_f32 v37, s[8:9], v38, v38, 1.0
	s_nop 0
	v_cndmask_b32_e32 v21, v36, v21, vcc
	v_rcp_f32_e32 v40, v37
	v_div_scale_f32 v36, s[10:11], v21, v21, 1.0
	v_rcp_f32_e32 v41, v36
	v_fma_f32 v43, -v37, v40, 1.0
	v_div_scale_f32 v39, s[8:9], 1.0, v38, 1.0
	v_fmac_f32_e32 v40, v43, v40
	v_fma_f32 v43, -v36, v41, 1.0
	v_div_scale_f32 v42, vcc, 1.0, v21, 1.0
	v_mul_f32_e32 v44, v39, v40
	v_fmac_f32_e32 v41, v43, v41
	v_fma_f32 v43, -v37, v44, v39
	v_mul_f32_e32 v45, v42, v41
	v_fmac_f32_e32 v44, v43, v40
	v_fma_f32 v43, -v36, v45, v42
	v_fmac_f32_e32 v45, v43, v41
	v_fma_f32 v36, -v36, v45, v42
	v_fma_f32 v37, -v37, v44, v39
	v_div_fmas_f32 v36, v36, v41, v45
	s_mov_b64 vcc, s[8:9]
	v_div_fixup_f32 v36, v36, v21, 1.0
	v_div_fmas_f32 v21, v37, v40, v44
	v_pk_mul_f32 v[34:35], v[36:37], v[34:35] op_sel_hi:[0,1]
	v_pk_mul_f32 v[32:33], v[36:37], v[32:33] op_sel_hi:[0,1]
	v_div_fixup_f32 v36, v21, v38, 1.0
	v_pk_mul_f32 v[22:23], v[22:23], v[34:35]
	v_pk_mul_f32 v[24:25], v[24:25], v[32:33]
	v_pk_mul_f32 v[30:31], v[36:37], v[30:31] op_sel_hi:[0,1]
	v_cvt_pk_bf16_f32 v22, v22, v23
	v_cvt_pk_bf16_f32 v23, v24, v25
	v_pk_mul_f32 v[24:25], v[28:29], v[30:31]
	global_store_dwordx2 v[26:27], v[22:23], off
	v_cvt_pk_bf16_f32 v21, v24, v25
	v_lshl_add_u64 v[22:23], s[50:51], 0, v[8:9]
	global_store_dword v[22:23], v21, off
	s_and_saveexec_b64 s[8:9], s[0:1]
	s_cbranch_execz .LBB0_1617
	v_lshl_add_u64 v[22:23], s[50:51], 0, v[6:7]
	v_add_co_u32_e32 v22, vcc, 0xe800000, v22
	v_lshlrev_b32_e32 v21, 16, v46
	v_lshlrev_b32_e32 v26, 16, v47
	v_mul_f32_e32 v27, v48, v26
	v_mul_f32_e32 v26, v49, v26
	v_fma_f32 v25, v49, v21, -v27
	v_fmac_f32_e32 v26, v48, v21
	v_bfe_u32 v21, v25, 16, 1
	v_addc_co_u32_e32 v23, vcc, 0, v23, vcc
	v_bfe_u32 v24, v26, 16, 1
	v_add3_u32 v21, v25, v21, s4
	v_add3_u32 v24, v26, v24, s4
	global_store_short_d16_hi v[22:23], v21, off
	global_store_short_d16_hi v[22:23], v24, off offset:32
	s_branch .LBB0_1617

; __global__ void __launch_bounds__(512, 2) fwd_mega(Args args) {
	.amdhsa_kernel _Z8fwd_mega4Args
		.amdhsa_group_segment_fixed_size 0
		.amdhsa_private_segment_fixed_size 0
		.amdhsa_kernarg_size 2160
		.amdhsa_user_sgpr_count 2
		.amdhsa_user_sgpr_dispatch_ptr 0
		.amdhsa_user_sgpr_queue_ptr 0
		.amdhsa_user_sgpr_kernarg_segment_ptr 1
		.amdhsa_user_sgpr_dispatch_id 0
		.amdhsa_user_sgpr_kernarg_preload_length 0
		.amdhsa_user_sgpr_kernarg_preload_offset 0
		.amdhsa_user_sgpr_private_segment_size 0
		.amdhsa_uses_dynamic_stack 0
		.amdhsa_enable_private_segment 0
		.amdhsa_system_sgpr_workgroup_id_x 1
		.amdhsa_system_sgpr_workgroup_id_y 0
		.amdhsa_system_sgpr_workgroup_id_z 0
		.amdhsa_system_sgpr_workgroup_info 0
		.amdhsa_system_vgpr_workitem_id 2
		.amdhsa_next_free_vgpr 255
		.amdhsa_next_free_sgpr 100
		.amdhsa_accum_offset 256
		.amdhsa_reserve_vcc 1
		.amdhsa_float_round_mode_32 0
		.amdhsa_float_round_mode_16_64 0
		.amdhsa_float_denorm_mode_32 3
		.amdhsa_float_denorm_mode_16_64 3
		.amdhsa_dx10_clamp 1
		.amdhsa_ieee_mode 1
		.amdhsa_fp16_overflow 0
		.amdhsa_tg_split 0
		.amdhsa_exception_fp_ieee_invalid_op 0
		.amdhsa_exception_fp_denorm_src 0
		.amdhsa_exception_fp_ieee_div_zero 0
		.amdhsa_exception_fp_ieee_overflow 0
		.amdhsa_exception_fp_ieee_underflow 0
		.amdhsa_exception_fp_ieee_inexact 0
		.amdhsa_exception_int_div_zero 0
	.end_amdhsa_kernel

; __global__ void __launch_bounds__(512, 2) fwd_mega(Args args) {
amdhsa.kernels:
  - .agpr_count:     0
    .args:
      - .offset:         0
        .size:           1904
        .value_kind:     by_value
      - .offset:         1904
        .size:           4
        .value_kind:     hidden_block_count_x
      - .offset:         1908
        .size:           4
        .value_kind:     hidden_block_count_y
      - .offset:         1912
        .size:           4
        .value_kind:     hidden_block_count_z
      - .offset:         1916
        .size:           2
        .value_kind:     hidden_group_size_x
      - .offset:         1918
        .size:           2
        .value_kind:     hidden_group_size_y
      - .offset:         1920
        .size:           2
        .value_kind:     hidden_group_size_z
      - .offset:         1922
        .size:           2
        .value_kind:     hidden_remainder_x
      - .offset:         1924
        .size:           2
        .value_kind:     hidden_remainder_y
      - .offset:         1926
        .size:           2
        .value_kind:     hidden_remainder_z
      - .offset:         1944
        .size:           8
        .value_kind:     hidden_global_offset_x
      - .offset:         1952
        .size:           8
        .value_kind:     hidden_global_offset_y
      - .offset:         1960
        .size:           8
        .value_kind:     hidden_global_offset_z
      - .offset:         1968
        .size:           2
        .value_kind:     hidden_grid_dims
      - .offset:         1992
        .size:           8
        .value_kind:     hidden_multigrid_sync_arg
      - .offset:         2024
        .size:           4
        .value_kind:     hidden_dynamic_lds_size
    .group_segment_fixed_size: 0
    .kernarg_segment_align: 8
    .kernarg_segment_size: 2160
    .language:       OpenCL C
    .language_version:
      - 2
      - 0
    .max_flat_workgroup_size: 512
    .name:           _Z8fwd_mega4Args
    .private_segment_fixed_size: 0
    .sgpr_count:     106
    .sgpr_spill_count: 36
    .symbol:         _Z8fwd_mega4Args.kd
    .uniform_work_group_size: 1
    .uses_dynamic_stack: false
    .vgpr_count:     255
    .vgpr_spill_count: 0
    .wavefront_size: 64
